# P3: ss1 row-norm loads issued at the tile top (before the K loop) into dead VGPRs; epilogue no longer waits vmcnt(0) for them; tile-top store-drain wait dropped in P3
# speedup vs baseline: 1.0022x; 1.0006x over previous
; template <class Epi>
; __device__ __forceinline__ void gemm_phase(LAS unsigned char* lds, const Gemm g, const StaticOrder& S, const Epi& E) {
;     ...
;         const bool has_next = S.next(ui + 1, nxt);
;         const char* nA = has_next ? (const char*)g.A + (size_t)nxt.pm * tstepA : cA; const char* nB = has_next ? (const char*)g.Bt + (size_t)nxt.pn * tstepB : cB;
;         for (int t = 0; t < nt; t += 2) {
;             const bool last = (t == nt - 2);
;             const char* a1 = cA + (size_t)(t + 1) * kstepA;
;             const char* a2 = last ? nA : cA + (size_t)(t + 2) * kstepA; const char* b2 = last ? nB : cB + (size_t)(t + 2) * kstep;
;             const char* a3 = a2 + kstepA; const char* b3 = b2 + kstep;
;             PG8_LDB(B0, 0, 0); PG8_LDB(B1, 0, 1); PG8_SCHED; PG8_LDA(At, 0, 0); PG8_STAGE(PG8_SA(1, 1), a1 + hstepA, voffA);
;             PG8_WAIT_V(8); PG8_WAIT_L(0); PG8_BAR; PG8_MMA(0, 0, At, B0); PG8_MMA(0, 1, At, B1); PG8_BAR; PG8_SCHED;
;             PG8_LDA(At, 0, 1); PG8_STAGE(PG8_SB(0, 0), b2, voffB); PG8_STAGE(PG8_SB(0, 1), b2 + hstepB, voffB); PG8_STAGE(PG8_SA(0, 0), a2, voffA);
;             PG8_WAIT_V(8); PG8_WAIT_L(0); PG8_BAR; PG8_MMA(1, 0, At, B0); PG8_MMA(1, 1, At, B1); PG8_BAR; PG8_SCHED;
;             PG8_LDB(B0, 1, 0); PG8_LDB(B1, 1, 1); PG8_SCHED; PG8_LDA(At, 1, 0); PG8_STAGE(PG8_SA(0, 1), a2 + hstepA, voffA);
;             PG8_WAIT_V(8); PG8_WAIT_L(0); PG8_BAR; PG8_MMA(0, 0, At, B0); PG8_MMA(0, 1, At, B1); PG8_BAR; PG8_SCHED;
;             PG8_LDA(At, 1, 1); PG8_STAGE(PG8_SB(1, 0), b3, voffB); PG8_STAGE(PG8_SB(1, 1), b3 + hstepB, voffB); PG8_STAGE(PG8_SA(1, 0), a3, voffA);
;             PG8_WAIT_V(8); PG8_WAIT_L(0); PG8_BAR; PG8_MMA(1, 0, At, B0); PG8_MMA(1, 1, At, B1); PG8_BAR; PG8_SCHED;
;         }
;         if (wr == 0) PG8_BAR;
;         E(acc, cur, wr, wc, fr, fq);
;         if (!has_next) break;
; #pragma unroll
;         for (int a = 0; a < 2; ++a)
; #pragma unroll
;             for (int b = 0; b < 2; ++b)
; #pragma unroll
;                 for (int m = 0; m < 4; ++m)
; #pragma unroll
;                     for (int n = 0; n < 2; ++n) acc[a][b][m][n] = (f32x4){0.f, 0.f, 0.f, 0.f};
;         cur = nxt; cA = nA; cB = nB; ++ui;
;     __device__ __forceinline__ void operator()(const Acc& acc, const Unit& u, int wr, int wc, int fr, int fq) const {
;     ...
;                 const float rs = rsqrtf(ss1[row] * (1.0f / DM) + EPS);
.LBB0_686:
	s_ashr_i32 s49, s48, 31
	s_lshl_b64 s[14:15], s[48:49], 19
	v_readlane_b32 s16, v254, 49
	v_readlane_b32 s17, v254, 50
	s_add_u32 s52, s16, s14
	s_addc_u32 s53, s17, s15
	s_and_b64 s[14:15], s[8:9], exec
	s_cselect_b32 s1, s53, s11
	s_cselect_b32 s3, s52, s10
	s_ashr_i32 s47, s46, 31
	s_lshl_b64 s[14:15], s[46:47], 19
	s_add_u32 s54, s34, s14
	s_addc_u32 s55, s35, s15
	s_and_b64 s[14:15], s[8:9], exec
	s_cselect_b32 s16, s55, s13
	s_cselect_b32 s17, s54, s12
	s_add_u32 s10, s10, 0x40080
	s_addc_u32 s11, s11, 0
	s_add_u32 s18, s12, 0x100
	v_mov_b32_e32 v0, 0
	s_addc_u32 s19, s13, 0
	s_mov_b32 s30, -2
	v_mov_b32_e32 v1, v0
	v_mov_b32_e32 v2, v0
	v_mov_b32_e32 v3, v0
	v_mov_b32_e32 v4, v0
	v_mov_b32_e32 v5, v0
	v_mov_b32_e32 v6, v0
	v_mov_b32_e32 v7, v0
	v_mov_b32_e32 v16, v0
	v_mov_b32_e32 v17, v0
	v_mov_b32_e32 v18, v0
	v_mov_b32_e32 v19, v0
	v_mov_b32_e32 v20, v0
	v_mov_b32_e32 v21, v0
	v_mov_b32_e32 v22, v0
	v_mov_b32_e32 v23, v0
	v_mov_b32_e32 v32, v0
	v_mov_b32_e32 v33, v0
	v_mov_b32_e32 v34, v0
	v_mov_b32_e32 v35, v0
	v_mov_b32_e32 v36, v0
	v_mov_b32_e32 v37, v0
	v_mov_b32_e32 v38, v0
	v_mov_b32_e32 v39, v0
	v_mov_b32_e32 v48, v0
	v_mov_b32_e32 v49, v0
	v_mov_b32_e32 v50, v0
	v_mov_b32_e32 v51, v0
	v_mov_b32_e32 v52, v0
	v_mov_b32_e32 v53, v0
	v_mov_b32_e32 v54, v0
	v_mov_b32_e32 v55, v0
	v_mov_b32_e32 v8, v0
	v_mov_b32_e32 v9, v0
	v_mov_b32_e32 v10, v0
	v_mov_b32_e32 v11, v0
	v_mov_b32_e32 v12, v0
	v_mov_b32_e32 v13, v0
	v_mov_b32_e32 v14, v0
	v_mov_b32_e32 v15, v0
	v_mov_b32_e32 v24, v0
	v_mov_b32_e32 v25, v0
	v_mov_b32_e32 v26, v0
	v_mov_b32_e32 v27, v0
	v_mov_b32_e32 v28, v0
	v_mov_b32_e32 v29, v0
	v_mov_b32_e32 v30, v0
	v_mov_b32_e32 v31, v0
	v_mov_b32_e32 v40, v0
	v_mov_b32_e32 v41, v0
	v_mov_b32_e32 v42, v0
	v_mov_b32_e32 v43, v0
	v_mov_b32_e32 v44, v0
	v_mov_b32_e32 v45, v0
	v_mov_b32_e32 v46, v0
	v_mov_b32_e32 v47, v0
	v_mov_b32_e32 v56, v0
	v_mov_b32_e32 v57, v0
	v_mov_b32_e32 v58, v0
	v_mov_b32_e32 v59, v0
	v_mov_b32_e32 v60, v0
	v_mov_b32_e32 v61, v0
	v_mov_b32_e32 v62, v0
	v_mov_b32_e32 v63, v0
	s_lshl_b32 s87, s2, 8
	s_add_i32 s87, s87, s61
	v_or_b32_e32 v250, s87, v145
	v_ashrrev_i32_e32 v251, 31, v250
	v_lshl_add_u64 v[252:253], v[250:251], 2, s[28:29]
	global_load_dword v238, v[252:253], off
	global_load_dword v239, v[252:253], off offset:64
	global_load_dword v240, v[252:253], off offset:128
	global_load_dword v241, v[252:253], off offset:192
	global_load_dword v242, v[252:253], off offset:512
	global_load_dword v246, v[252:253], off offset:576
	global_load_dword v247, v[252:253], off offset:640
	global_load_dword v248, v[252:253], off offset:704
	v_mov_b32_e32 v64, v0
	v_mov_b32_e32 v65, v0
	v_mov_b32_e32 v66, v0
	v_mov_b32_e32 v67, v0
	v_mov_b32_e32 v68, v0
	v_mov_b32_e32 v69, v0
	v_mov_b32_e32 v70, v0
	v_mov_b32_e32 v71, v0
	v_mov_b32_e32 v80, v0
	v_mov_b32_e32 v81, v0
	v_mov_b32_e32 v82, v0
	v_mov_b32_e32 v83, v0
	v_mov_b32_e32 v84, v0
	v_mov_b32_e32 v85, v0
	v_mov_b32_e32 v86, v0
	v_mov_b32_e32 v87, v0
	v_mov_b32_e32 v96, v0
	v_mov_b32_e32 v97, v0
	v_mov_b32_e32 v98, v0
	v_mov_b32_e32 v99, v0
	v_mov_b32_e32 v100, v0
	v_mov_b32_e32 v101, v0
	v_mov_b32_e32 v102, v0
	v_mov_b32_e32 v103, v0
	v_mov_b32_e32 v112, v0
	v_mov_b32_e32 v113, v0
	v_mov_b32_e32 v114, v0
	v_mov_b32_e32 v115, v0
	v_mov_b32_e32 v116, v0
	v_mov_b32_e32 v117, v0
	v_mov_b32_e32 v118, v0
	v_mov_b32_e32 v119, v0
	v_mov_b32_e32 v72, v0
	v_mov_b32_e32 v73, v0
	v_mov_b32_e32 v74, v0
	v_mov_b32_e32 v75, v0
	v_mov_b32_e32 v76, v0
	v_mov_b32_e32 v77, v0
	v_mov_b32_e32 v78, v0
	v_mov_b32_e32 v79, v0
	v_mov_b32_e32 v88, v0
	v_mov_b32_e32 v89, v0
	v_mov_b32_e32 v90, v0
	v_mov_b32_e32 v91, v0
	v_mov_b32_e32 v92, v0
	v_mov_b32_e32 v93, v0
	v_mov_b32_e32 v94, v0
	v_mov_b32_e32 v95, v0
	v_mov_b32_e32 v104, v0
	v_mov_b32_e32 v105, v0
	v_mov_b32_e32 v106, v0
	v_mov_b32_e32 v107, v0
	v_mov_b32_e32 v108, v0
	v_mov_b32_e32 v109, v0
	v_mov_b32_e32 v110, v0
	v_mov_b32_e32 v111, v0
	v_mov_b32_e32 v120, v0
	v_mov_b32_e32 v121, v0
	v_mov_b32_e32 v122, v0
	v_mov_b32_e32 v123, v0
	v_mov_b32_e32 v124, v0
	v_mov_b32_e32 v125, v0
	v_mov_b32_e32 v126, v0
	v_mov_b32_e32 v127, v0

; __device__ __forceinline__ float fast_sigmoid(float a) { return __builtin_amdgcn_rcpf(1.0f + __expf(-a)); }
;     __device__ __forceinline__ void operator()(const Acc& acc, const Unit& u, int wr, int wc, int fr, int fq) const {
;     ...
;                 const int row = u.pm * 256 + ai * 128 + wr * 64 + m * 16 + fr;
;                 const float rs = rsqrtf(ss1[row] * (1.0f / DM) + EPS);
;                 const int posidx = row < MPROMPT ? (row & 2047) : 2048;
;                 f32x4 v[2][2];
; #pragma unroll
;                 for (int bj = 0; bj < 2; ++bj)
; #pragma unroll
;                     for (int n = 0; n < 2; ++n) v[bj][n] = acc[ai][bj][m][n] * rs;
;     ...
;                 } else if (kind == 7) {
; #pragma unroll
;                     for (int bj = 0; bj < 2; ++bj)
; #pragma unroll
;                         for (int n = 0; n < 2; ++n)
; #pragma unroll
;                             for (int j = 0; j < 4; ++j) v[bj][n][j] = fast_sigmoid(v[bj][n][j]);
.LBB0_694:
	v_sub_co_u32_e64 v128, s[10:11], s49, 1
	s_and_b64 s[12:13], s[10:11], exec
	s_cselect_b32 s19, s23, s25
	s_cselect_b32 s18, s22, s24
	s_lshl_b32 s87, s2, 8
	s_add_i32 s87, s87, s61
	v_or_b32_e32 v160, s87, v145
	v_ashrrev_i32_e32 v161, 31, v160
	v_readfirstlane_b32 s47, v128
	v_lshl_add_u64 v[128:129], v[160:161], 2, s[28:29]
	v_mov_b32_e32 v181, v239
	v_mov_b32_e32 v182, v240
	v_mov_b32_e32 v183, v241
	v_mov_b32_e32 v184, v242
	v_mov_b32_e32 v185, v246
	v_mov_b32_e32 v186, v247
	v_mov_b32_e32 v187, v248
	v_mov_b32_e32 v128, v238
	s_cmp_gt_u32 s49, 1
	s_cselect_b64 s[14:15], -1, 0
	s_add_i32 s1, s49, -3
	s_cmp_gt_u32 s1, 1
	s_cselect_b64 s[16:17], -1, 0
	s_cmp_eq_u32 s49, 4
	s_cselect_b64 vcc, -1, 0
	v_cndmask_b32_e32 v156, 1.0, v175, vcc
	v_bitop3_b32 v161, s87, v176, v145 bitop3:0xc8
	v_cmp_lt_i32_e64 s[12:13], s75, v160
	s_mov_b64 s[2:3], -1
	s_nop 0
	v_fmamk_f32 v128, v128, 0x3a800000, v174
	v_cmp_gt_f32_e32 vcc, s74, v128
	v_mul_f32_e32 v129, 0x4b800000, v128
	s_nop 0
	v_cndmask_b32_e32 v128, v128, v129, vcc
	v_rsq_f32_e32 v128, v128
	s_nop 0
	v_mul_f32_e32 v129, 0x45800000, v128
	v_cndmask_b32_e32 v132, v128, v129, vcc
	v_cmp_gt_i32_e32 vcc, s64, v160
	v_pk_mul_f32 v[162:163], v[126:127], v[132:133] op_sel_hi:[1,0]
	v_pk_mul_f32 v[166:167], v[124:125], v[132:133] op_sel_hi:[1,0]
	v_pk_mul_f32 v[136:137], v[122:123], v[132:133] op_sel_hi:[1,0]
	v_pk_mul_f32 v[164:165], v[120:121], v[132:133] op_sel_hi:[1,0]
	v_pk_mul_f32 v[130:131], v[118:119], v[132:133] op_sel_hi:[1,0]
	v_pk_mul_f32 v[134:135], v[116:117], v[132:133] op_sel_hi:[1,0]
	v_pk_mul_f32 v[128:129], v[114:115], v[132:133] op_sel_hi:[1,0]
	v_pk_mul_f32 v[132:133], v[112:113], v[132:133] op_sel_hi:[1,0]
	v_cndmask_b32_e32 v155, v177, v161, vcc
	s_and_b64 vcc, exec, s[14:15]
	s_cbranch_vccz .LBB0_705
	s_and_b64 vcc, exec, s[16:17]
	s_cbranch_vccz .LBB0_702
	s_cmp_gt_i32 s49, 6
	s_cbranch_scc0 .LBB0_698
	v_mul_f32_e32 v112, 0xbfb8aa3b, v166
	v_exp_f32_e32 v112, v112
	v_mul_f32_e32 v113, 0xbfb8aa3b, v167
	v_exp_f32_e32 v113, v113
	v_mul_f32_e32 v114, 0xbfb8aa3b, v163
	v_add_f32_e32 v112, 1.0, v112
	v_rcp_f32_e32 v116, v112
	v_mul_f32_e32 v112, 0xbfb8aa3b, v162
	v_exp_f32_e32 v112, v112
	v_exp_f32_e32 v114, v114
	v_add_f32_e32 v113, 1.0, v113
	v_rcp_f32_e32 v117, v113
	v_add_f32_e32 v112, 1.0, v112
	v_mul_f32_e32 v113, 0xbfb8aa3b, v164
	v_rcp_f32_e32 v118, v112
	v_add_f32_e32 v112, 1.0, v114
	v_exp_f32_e32 v113, v113
	v_mul_f32_e32 v114, 0xbfb8aa3b, v165
	v_exp_f32_e32 v114, v114
	v_rcp_f32_e32 v119, v112
	v_add_f32_e32 v112, 1.0, v113
	v_mul_f32_e32 v113, 0xbfb8aa3b, v136
	v_rcp_f32_e32 v124, v112
	v_add_f32_e32 v112, 1.0, v114
	v_exp_f32_e32 v113, v113
	v_mul_f32_e32 v114, 0xbfb8aa3b, v137
	v_exp_f32_e32 v114, v114
	v_rcp_f32_e32 v125, v112
	v_add_f32_e32 v112, 1.0, v113
	v_rcp_f32_e32 v126, v112
	v_add_f32_e32 v112, 1.0, v114
	v_mul_f32_e32 v113, 0xbfb8aa3b, v134
	v_mul_f32_e32 v114, 0xbfb8aa3b, v135
	v_exp_f32_e32 v113, v113
	v_exp_f32_e32 v114, v114
	v_rcp_f32_e32 v127, v112
	v_mul_f32_e32 v115, 0xbfb8aa3b, v131
	v_add_f32_e32 v112, 1.0, v113
	v_add_f32_e32 v113, 1.0, v114
	v_mul_f32_e32 v114, 0xbfb8aa3b, v130
	v_mul_f32_e32 v120, 0xbfb8aa3b, v132
	v_mul_f32_e32 v121, 0xbfb8aa3b, v133
	v_mul_f32_e32 v122, 0xbfb8aa3b, v128
	v_mul_f32_e32 v123, 0xbfb8aa3b, v129
	v_exp_f32_e32 v114, v114
	v_exp_f32_e32 v115, v115
	v_exp_f32_e32 v120, v120
	v_exp_f32_e32 v121, v121
	v_exp_f32_e32 v122, v122
	v_exp_f32_e32 v123, v123
	v_add_f32_e32 v114, 1.0, v114
	v_add_f32_e32 v115, 1.0, v115
	v_add_f32_e32 v120, 1.0, v120
	v_add_f32_e32 v121, 1.0, v121
	v_add_f32_e32 v122, 1.0, v122
	v_add_f32_e32 v123, 1.0, v123
	v_rcp_f32_e32 v112, v112
	v_rcp_f32_e32 v113, v113
	v_rcp_f32_e32 v114, v114
	v_rcp_f32_e32 v115, v115
	v_rcp_f32_e32 v120, v120
	v_rcp_f32_e32 v121, v121
	v_rcp_f32_e32 v122, v122
	v_rcp_f32_e32 v123, v123
	s_mov_b64 s[2:3], 0
